# v45 + LRU input GEMM column rounds reversed (gate half first, x half last) so the conv phase reads the most recently written x columns
# baseline (speedup 1.0000x reference)
;     __device__ bool next(int i, Unit& u) const {
;         const long L = (long)i * G + c; if (L >= nwg) return false;
;         int wgid = (int)L; { const int q = nwg / NXCD, r = nwg % NXCD, xcd = wgid % NXCD, off = wgid / NXCD; wgid = (xcd < r ? xcd * (q + 1) : r * (q + 1) + (xcd - r) * q) + off; }
;         const int nig = WGM * nN, gid = wgid / nig, fm = gid * WGM, gsz = (nM - fm) < WGM ? (nM - fm) : WGM;
;         u.pm = fm + ((wgid % nig) % gsz); u.pn = (wgid % nig) / gsz; return true;
.LBB0_400:
	s_ashr_i32 s1, s1, 3
	s_add_i32 s1, s8, s1
	s_xor_b32 s1, s1, 0x20
	s_bfe_u32 s100, s1, 0x10006
	s_bfe_u32 s101, s1, 0x40002
	s_andn2_b32 s1, s1, 0x7c
	s_lshl_b32 s100, s100, 2
	s_lshl_b32 s101, s101, 3
	s_or_b32 s1, s1, s100
	s_or_b32 s1, s1, s101
	s_ashr_i32 s3, s1, 31
	s_lshr_b32 s3, s3, 25
	s_add_i32 s3, s1, s3
	s_ashr_i32 s6, s3, 7
	s_and_b32 s3, s3, 0xff80
	s_sub_i32 s1, s1, s3
	s_bfe_i32 s3, s1, 0x80000
	s_bfe_u32 s3, s3, 0x3000c
	s_add_i32 s3, s1, s3
	s_bfe_i32 s7, s3, 0x80000
	s_and_b32 s3, s3, 0xf8
	s_sub_i32 s1, s1, s3
	s_lshl_b32 s6, s6, 3
	s_sext_i32_i16 s7, s7
	s_sext_i32_i8 s1, s1
	s_add_i32 s8, s6, s1
	s_ashr_i32 s6, s7, 3

;     __device__ bool next(int i, Unit& u) const {
;         const long L = (long)i * G + c; if (L >= nwg) return false;
;         int wgid = (int)L; { const int q = nwg / NXCD, r = nwg % NXCD, xcd = wgid % NXCD, off = wgid / NXCD; wgid = (xcd < r ? xcd * (q + 1) : r * (q + 1) + (xcd - r) * q) + off; }
;         const int nig = WGM * nN, gid = wgid / nig, fm = gid * WGM, gsz = (nM - fm) < WGM ? (nM - fm) : WGM;
;         u.pm = fm + ((wgid % nig) % gsz); u.pn = (wgid % nig) / gsz; return true;
; template <class Epi>
; __device__ __forceinline__ void gemm_phase(LAS unsigned char* lds, const Gemm g, const StaticOrder& S, const Epi& E) {
;     ...
;         const bool has_next = S.next(ui + 1, nxt);
.LBB0_412:
	s_ashr_i32 s0, s0, 3
	s_add_i32 s0, s3, s0
	s_xor_b32 s0, s0, 0x20
	s_bfe_u32 s100, s0, 0x10006
	s_bfe_u32 s101, s0, 0x40002
	s_andn2_b32 s0, s0, 0x7c
	s_lshl_b32 s100, s100, 2
	s_lshl_b32 s101, s101, 3
	s_or_b32 s0, s0, s100
	s_or_b32 s0, s0, s101
	s_ashr_i32 s1, s0, 31
	s_lshr_b32 s1, s1, 25
	s_add_i32 s1, s0, s1
	s_ashr_i32 s3, s1, 7
	s_lshl_b32 s3, s3, 3
	s_sub_i32 s7, 32, s3
	s_min_i32 s7, s7, 8
	s_abs_i32 s9, s7
	v_cvt_f32_u32_e32 v2, s9
	s_sub_i32 s19, 0, s9
	s_and_b32 s1, s1, 0xffffff80
	s_sub_i32 s0, s0, s1
	v_rcp_iflag_f32_e32 v2, v2
	s_abs_i32 s1, s0
	s_xor_b32 s18, s0, s7
	s_ashr_i32 s18, s18, 31
	v_mul_f32_e32 v2, 0x4f7ffffe, v2
	v_cvt_u32_f32_e32 v2, v2
	s_nop 0
	v_readfirstlane_b32 s20, v2
	s_mul_i32 s19, s19, s20
	s_mul_hi_u32 s19, s20, s19
	s_add_i32 s20, s20, s19
	s_mul_hi_u32 s19, s1, s20
	s_mul_i32 s20, s19, s9
	s_sub_i32 s1, s1, s20
	s_add_i32 s21, s19, 1
	s_sub_i32 s20, s1, s9
	s_cmp_ge_u32 s1, s9
	s_cselect_b32 s19, s21, s19
	s_cselect_b32 s1, s20, s1
	s_add_i32 s20, s19, 1
	s_cmp_ge_u32 s1, s9
	s_cselect_b32 s1, s20, s19
	s_xor_b32 s1, s1, s18
	s_sub_i32 s18, s1, s18
	s_mul_i32 s1, s18, s7
	s_sub_i32 s0, s0, s1
	s_add_i32 s20, s3, s0
